# P4 ret_out_item: next-item tile loads issued later in the item (saddr form), norm weights fetched at item start
# speedup vs baseline: 1.0206x; 1.0024x over previous
.LBB0_455:
	v_or_b32_e32 v31, s25, v101
	v_sub_u32_e32 v32, v99, v31
	v_sub_u32_e32 v33, 0, v32
	v_max_i32_e32 v32, v32, v33
	v_cvt_f32_u32_e32 v59, v32
	v_or_b32_e32 v32, 1, v31
	v_sub_u32_e32 v33, v99, v32
	v_sub_u32_e32 v34, 0, v33
	v_max_i32_e32 v33, v33, v34
	v_cvt_f32_u32_e32 v60, v33
	v_or_b32_e32 v33, 2, v31
	v_sub_u32_e32 v34, v99, v33
	v_sub_u32_e32 v35, 0, v34
	v_max_i32_e32 v34, v34, v35
	v_cvt_f32_u32_e32 v61, v34
	v_or_b32_e32 v34, 3, v31
	s_lshl_b32 s10, s8, 22
	v_sub_u32_e32 v35, v99, v34
	s_and_b32 s10, s10, 0x1c00000
	v_sub_u32_e32 v36, 0, v35
	s_add_u32 s10, s86, s10
	v_max_i32_e32 v35, v35, v36
	s_addc_u32 s11, s87, 0
	v_cvt_f32_u32_e32 v62, v35
	v_sub_u32_e32 v35, v107, v31
	s_add_u32 s12, s10, 0x4000000
	v_sub_u32_e32 v36, 0, v35
	s_addc_u32 s13, s11, 0
	s_ashr_i32 s14, s8, 3
	v_max_i32_e32 v35, v35, v36
	s_ashr_i32 s15, s14, 31
	v_cvt_f32_u32_e32 v63, v35
	v_sub_u32_e32 v35, v107, v32
	s_lshl_b64 s[14:15], s[14:15], 13
	v_sub_u32_e32 v36, 0, v35
	v_lshl_add_u64 v[2:3], s[14:15], 0, v[68:69]
	v_max_i32_e32 v35, v35, v36
	v_lshlrev_b64 v[2:3], 1, v[2:3]
	s_add_u32 s16, s10, 0x2000000
	v_cvt_f32_u32_e32 v64, v35
	v_sub_u32_e32 v35, v107, v33
	v_lshl_add_u64 v[4:5], s[12:13], 0, v[2:3]
	s_addc_u32 s17, s11, 0
	v_sub_u32_e32 v36, 0, v35
	v_lshl_add_u64 v[6:7], s[16:17], 0, v[2:3]
	global_load_dwordx4 v[14:17], v[4:5], off
	global_load_dwordx4 v[10:13], v[6:7], off
	v_lshl_add_u64 v[4:5], s[14:15], 0, v[66:67]
	v_max_i32_e32 v35, v35, v36
	v_lshlrev_b64 v[4:5], 1, v[4:5]
	v_lshlrev_b32_e32 v0, 1, v104
	v_add_u32_e32 v27, 1, v76
	v_cvt_f32_u32_e32 v65, v35
	v_sub_u32_e32 v35, v107, v34
	v_lshl_add_u64 v[6:7], s[12:13], 0, v[4:5]
	v_and_b32_e32 v0, 0x70, v0
	s_add_i32 s12, 0, 0x12000
	v_cvt_f32_i32_e32 v43, v27
	v_sub_u32_e32 v27, 0x80, v76
	s_movk_i32 s13, 0x90
	v_sub_u32_e32 v36, 0, v35
	v_add_u32_e32 v26, 0, v0
	v_add_u32_e32 v0, s12, v0
	v_cvt_f32_i32_e32 v52, v27
	v_mul_lo_u32 v27, v76, s13
	v_max_i32_e32 v35, v35, v36
	v_add_u32_e32 v53, v26, v27
	v_add_u32_e32 v54, v0, v27
	v_ashrrev_i32_e32 v27, 3, v74
	v_cvt_f32_u32_e32 v74, v35
	v_sub_u32_e32 v35, v105, v31
	v_sub_u32_e32 v36, 0, v35
	v_max_i32_e32 v35, v35, v36
	v_cvt_f32_u32_e32 v76, v35
	v_sub_u32_e32 v35, v105, v32
	v_lshl_add_u64 v[2:3], s[10:11], 0, v[2:3]
	v_sub_u32_e32 v36, 0, v35
	global_load_dwordx4 v[18:21], v[2:3], off
	global_load_dwordx4 v[22:25], v[6:7], off
	v_lshl_add_u64 v[2:3], s[16:17], 0, v[4:5]
	v_lshl_add_u64 v[4:5], s[10:11], 0, v[4:5]
	v_add_u32_e32 v28, 1, v27
	v_max_i32_e32 v35, v35, v36
	global_load_dwordx4 v[6:9], v[2:3], off
	s_nop 0
	global_load_dwordx4 v[2:5], v[4:5], off
	v_cvt_f32_i32_e32 v55, v28
	v_sub_u32_e32 v28, 0x80, v27
	v_mul_lo_u32 v27, v27, s13
	v_cvt_f32_u32_e32 v77, v35
	v_sub_u32_e32 v35, v105, v33
	v_add_u32_e32 v58, v0, v27
	v_lshlrev_b32_e32 v0, 1, v100
	v_sub_u32_e32 v36, 0, v35
	v_add_u32_e32 v42, 0, v0
	v_max_i32_e32 v35, v35, v36
	v_mad_u64_u32 v[44:45], s[10:11], v78, s13, v[42:43]
	v_cvt_f32_u32_e32 v78, v35
	v_sub_u32_e32 v35, v105, v34
	v_sub_u32_e32 v36, 0, v35
	v_max_i32_e32 v35, v35, v36
	v_cvt_f32_u32_e32 v79, v35
	v_sub_u32_e32 v35, v103, v31
	v_sub_u32_e32 v36, 0, v35
	v_max_i32_e32 v35, v35, v36
	v_cvt_f32_u32_e32 v80, v35
	v_sub_u32_e32 v35, v103, v32
	v_sub_u32_e32 v36, 0, v35
	v_max_i32_e32 v35, v35, v36
	v_cvt_f32_u32_e32 v81, v35
	v_sub_u32_e32 v35, v103, v33
	v_sub_u32_e32 v36, 0, v35
	v_max_i32_e32 v35, v35, v36
	v_cvt_f32_u32_e32 v82, v35
	v_sub_u32_e32 v35, v103, v34
	v_sub_u32_e32 v36, 0, v35
	v_add_u32_e32 v57, v26, v27
	v_or_b32_e32 v26, 64, v99
	v_max_i32_e32 v35, v35, v36
	v_cvt_f32_u32_e32 v83, v35
	v_sub_u32_e32 v35, v26, v31
	v_sub_u32_e32 v36, 0, v35
	v_max_i32_e32 v35, v35, v36
	v_cvt_f32_u32_e32 v84, v35
	v_sub_u32_e32 v35, v26, v32
	v_sub_u32_e32 v36, 0, v35
	v_max_i32_e32 v35, v35, v36
	v_cvt_f32_u32_e32 v85, v35
	v_sub_u32_e32 v35, v26, v33
	v_sub_u32_e32 v36, 0, v35
	v_max_i32_e32 v35, v35, v36
	v_sub_u32_e32 v26, v26, v34
	v_cvt_f32_u32_e32 v86, v35
	v_sub_u32_e32 v35, 0, v26
	v_or_b32_e32 v27, 0x50, v99
	v_max_i32_e32 v26, v26, v35
	v_cvt_f32_u32_e32 v87, v26
	v_sub_u32_e32 v26, v27, v31
	v_sub_u32_e32 v35, 0, v26
	v_max_i32_e32 v26, v26, v35
	v_cvt_f32_u32_e32 v88, v26
	v_sub_u32_e32 v26, v27, v32
	v_sub_u32_e32 v35, 0, v26
	v_max_i32_e32 v26, v26, v35
	v_cvt_f32_u32_e32 v89, v26
	v_sub_u32_e32 v26, v27, v33
	v_sub_u32_e32 v35, 0, v26
	v_max_i32_e32 v26, v26, v35
	v_cvt_f32_u32_e32 v90, v26
	v_sub_u32_e32 v26, v27, v34
	v_sub_u32_e32 v27, 0, v26
	v_cvt_f32_i32_e32 v56, v28
	v_or_b32_e32 v28, 0x60, v99
	v_max_i32_e32 v26, v26, v27
	v_cvt_f32_u32_e32 v91, v26
	v_sub_u32_e32 v26, v28, v31
	v_sub_u32_e32 v27, 0, v26
	v_max_i32_e32 v26, v26, v27
	v_cvt_f32_u32_e32 v92, v26
	v_sub_u32_e32 v26, v28, v32
	v_sub_u32_e32 v27, 0, v26
	v_max_i32_e32 v26, v26, v27
	v_cvt_f32_u32_e32 v93, v26
	v_sub_u32_e32 v26, v28, v33
	v_sub_u32_e32 v27, 0, v26
	v_max_i32_e32 v26, v26, v27
	v_cvt_f32_u32_e32 v94, v26
	v_sub_u32_e32 v26, v28, v34
	v_sub_u32_e32 v27, 0, v26
	v_or_b32_e32 v29, 0x70, v102
	v_max_i32_e32 v26, v26, v27
	v_cvt_f32_u32_e32 v95, v26
	v_sub_u32_e32 v26, v29, v31
	v_sub_u32_e32 v27, 0, v26
	v_max_i32_e32 v26, v26, v27
	v_cvt_f32_u32_e32 v102, v26
	v_sub_u32_e32 v26, v29, v32
	v_sub_u32_e32 v27, 0, v26
	v_max_i32_e32 v26, v26, v27
	v_cvt_f32_u32_e32 v103, v26
	v_sub_u32_e32 v26, v29, v33
	v_sub_u32_e32 v27, 0, v26
	v_max_i32_e32 v26, v26, v27
	v_cvt_f32_u32_e32 v104, v26
	v_sub_u32_e32 v26, v29, v34
	v_sub_u32_e32 v27, 0, v26
	v_max_i32_e32 v26, v26, v27
	s_andn2_b32 s25, s25, 63
	v_cvt_f32_u32_e32 v105, v26
	v_or_b32_e32 v26, s25, v99
	v_readlane_b32 s11, v255, 22
	v_mul_lo_u32 v32, v26, s18
	v_or_b32_e32 v37, 64, v100
	v_add_u32_e32 v34, s11, v0
	v_add_u32_e32 v0, s11, v32
	v_mul_u32_u24_e32 v30, 0x90, v29
	v_mul_u32_u24_e32 v27, 0x110, v29
	v_add_u32_e32 v28, 0x1100, v0
	v_add_u32_e32 v29, 0x2200, v0
	v_add_u32_e32 v36, 0x3300, v0
	v_or_b32_e32 v38, v37, v108
	v_lshlrev_b32_e32 v37, 1, v37
	v_mul_u32_u24_e32 v33, 0x90, v114
	v_add_u32_e32 v112, v0, v37
	v_add_u32_e32 v113, v28, v37
	v_add_u32_e32 v114, v29, v37
	v_add_u32_e32 v115, v36, v37
	v_or_b32_e32 v37, 0x60, v100
	s_add_i32 s10, s11, s27
	s_add_i32 s12, s12, s26
	v_or_b32_e32 v39, v37, v108
	v_lshlrev_b32_e32 v37, 1, v37
	v_add_u32_e32 v45, s10, v100
	v_lshl_add_u32 v31, v116, 1, s12
	v_add_u32_e32 v107, v0, v125
	v_add_u32_e32 v111, v36, v125
	v_add_u32_e32 v100, v0, v37
	v_add_u32_e32 v118, v36, v37
	v_mul_lo_u32 v36, v26, s13
	v_and_b32_e32 v26, 48, v117
	v_or_b32_e32 v0, s25, v101
	v_readlane_b32 s12, v255, 27
	v_mul_lo_u32 v40, v0, s18
	v_lshlrev_b32_e32 v0, 2, v26
	v_readlane_b32 s13, v255, 28
	s_lshl_b32 s10, s24, 6
	v_ashrrev_i32_e32 v46, 2, v70
	v_lshl_add_u64 v[48:49], s[12:13], 0, v[0:1]
	v_readlane_b32 s12, v254, 0
	v_readlane_b32 s13, v254, 1
	s_add_i32 s10, s10, 0
	s_load_dword s73, s[12:13], 0x98
	v_add_u32_e32 v109, v28, v125
	v_add_u32_e32 v108, v28, v37
	v_add_u32_e32 v116, v29, v37
	v_lshl_add_u32 v37, v99, 2, s10
	v_mul_lo_u32 v28, v46, s18
	s_lshl_b64 s[10:11], s[8:9], 14
	v_add_u32_e32 v110, v29, v125
	v_add3_u32 v70, 0, v28, v0
	v_mov_b32_e32 v29, s11
	v_or_b32_e32 v0, s10, v72
	v_lshlrev_b32_e32 v28, 7, v99
	s_lshl_b32 s9, s24, 11
	v_readlane_b32 s10, v255, 12
	v_mul_u32_u24_e32 v35, 0x90, v132
	v_mul_u32_u24_e32 v38, 0x90, v38
	v_mul_u32_u24_e32 v39, 0x90, v39
	v_or3_b32 v28, s9, v28, v0
	v_readlane_b32 s11, v255, 13
	v_readlane_b32 s70, v255, 32
	v_readlane_b32 s66, v255, 34
	v_readlane_b32 s60, v255, 36
	v_readlane_b32 s62, v255, 38
	v_readlane_b32 s64, v255, 40
	v_readlane_b32 s34, v255, 42
	v_readlane_b32 s52, v255, 44
	v_readlane_b32 s54, v255, 46
	v_readlane_b32 s58, v255, 48
	v_ashrrev_i32_e32 v47, 31, v46
	v_lshl_add_u64 v[50:51], s[10:11], 0, v[28:29]
	s_lshl_b64 s[10:11], s[2:3], 14
	v_add_u32_e32 v72, v42, v30
	v_add_u32_e32 v99, v45, v27
	v_add_u32_e32 v101, v31, v33
	v_add_u32_e32 v117, v34, v32
	v_add_u32_e32 v119, v31, v35
	v_add_u32_e32 v120, v31, v38
	v_add_u32_e32 v121, v31, v39
	v_add_u32_e32 v106, v106, v36
	v_lshlrev_b32_e32 v0, 1, v26
	v_add_u32_e32 v122, v37, v40
	v_readlane_b32 s69, v255, 31
	v_readlane_b32 s71, v255, 33
	v_readlane_b32 s67, v255, 35
	v_readlane_b32 s61, v255, 37
	v_readlane_b32 s63, v255, 39
	v_readlane_b32 s65, v255, 41
	v_readlane_b32 s35, v255, 43
	v_readlane_b32 s53, v255, 45
	v_readlane_b32 s55, v255, 47
	v_readlane_b32 s59, v255, 49
	v_readlane_b32 s14, v255, 29
	v_readlane_b32 s15, v255, 30
	s_waitcnt vmcnt(0)
	v_lshlrev_b32_e32 v236, 4, v214
	v_add_u32_e32 v237, 0x2000000, v236
	v_add_u32_e32 v238, 0x4000000, v236
	v_add_u32_e32 v239, 0x2000, v236
	v_add_u32_e32 v240, 0x2002000, v236
	v_add_u32_e32 v241, 0x4002000, v236
	s_branch .LBB0_457
.LBB0_456:
	ds_read_b128 v[26:29], v44 offset:55296
	v_add_u32_e32 v144, v42, v75
	ds_read_b128 v[30:33], v144
	ds_read_b128 v[124:127], v44 offset:55360
	ds_read_b128 v[34:37], v144 offset:64
	ds_read_b128 v[38:41], v144 offset:2304
	ds_read_b128 v[128:131], v144 offset:2368
	v_add_u32_e32 v145, v42, v96
	v_mul_f32_e32 v160, v123, v65
	v_exp_f32_e32 v160, v160
	s_ashr_i32 s14, s8, 3
	s_ashr_i32 s15, s14, 31
	s_waitcnt lgkmcnt(1)
	v_mfma_f32_16x16x32_bf16 v[132:135], v[26:29], v[38:41], 0
	ds_read_b128 v[38:41], v144 offset:4608
	ds_read_b128 v[136:139], v144 offset:4672
	s_lshl_b64 s[14:15], s[14:15], 7
	s_lshl_b32 s8, s9, 22
	s_waitcnt lgkmcnt(1)
	v_mfma_f32_16x16x32_bf16 v[140:143], v[26:29], v[38:41], 0
	ds_read_b128 v[38:41], v145
	ds_read_b128 v[152:155], v145 offset:64
	s_add_u32 s16, s86, s8
	s_addc_u32 s17, s87, 0
	s_waitcnt lgkmcnt(1)
	v_mfma_f32_16x16x32_bf16 v[156:159], v[26:29], v[38:41], 0
	ds_read_b128 v[38:41], v144 offset:9216
	ds_read_b128 v[162:165], v144 offset:9280
	s_mov_b32 s8, 0x6000000
	s_lshl_b32 s80, s9, 8
	s_waitcnt lgkmcnt(1)
	v_mfma_f32_16x16x32_bf16 v[166:169], v[26:29], v[38:41], 0
	ds_read_b128 v[38:41], v144 offset:11520
	ds_read_b128 v[170:173], v144 offset:11584
	s_waitcnt lgkmcnt(1)
	v_mfma_f32_16x16x32_bf16 v[174:177], v[26:29], v[38:41], 0
	ds_read_b128 v[38:41], v144 offset:13824
	ds_read_b128 v[198:201], v72
	ds_read_b128 v[202:205], v144 offset:13888
	v_add_co_u32_e32 v144, vcc, 0xffffe000, v50
	v_mfma_f32_16x16x32_bf16 v[30:33], v[26:29], v[30:33], 0
	s_nop 0
	v_addc_co_u32_e32 v145, vcc, -1, v51, vcc
	ds_read_b128 v[210:213], v72 offset:64
	v_mfma_f32_16x16x32_bf16 v[128:131], v[124:127], v[128:131], v[132:135]
	v_mfma_f32_16x16x32_bf16 v[132:135], v[124:127], v[136:139], v[140:143]
	v_mul_f32_e32 v136, v123, v60
	s_nop 5
	v_mul_f32_e32 v130, v160, v130
	v_mul_f32_e32 v140, v123, v61
	s_waitcnt lgkmcnt(3)
	v_mfma_f32_16x16x32_bf16 v[206:209], v[26:29], v[38:41], 0
	v_exp_f32_e32 v147, v140
	v_mul_f32_e32 v140, v123, v62
	s_waitcnt lgkmcnt(2)
	v_mfma_f32_16x16x32_bf16 v[198:201], v[26:29], v[198:201], 0
	v_mul_f32_e32 v26, v123, v59
	v_mfma_f32_16x16x32_bf16 v[216:219], v[124:127], v[34:37], v[30:33]
	global_load_dwordx4 v[38:41], v[144:145], off offset:-64
	global_load_dwordx4 v[34:37], v[144:145], off
	v_exp_f32_e32 v144, v26
	v_exp_f32_e32 v145, v136
	v_mfma_f32_16x16x32_bf16 v[136:139], v[124:127], v[152:155], v[156:159]
	v_exp_f32_e32 v152, v140
	s_nop 1
	v_mul_f32_e32 v144, v144, v216
	v_mul_f32_e32 v145, v145, v217
	v_mul_f32_e32 v147, v147, v218
	v_mul_f32_e32 v156, v152, v219
	v_cvt_pk_bf16_f32 v144, v144, v145
	v_cvt_pk_bf16_f32 v145, v147, v156
	v_add_u32_e32 v147, v45, v71
	global_load_dwordx4 v[30:33], v[50:51], off offset:-64
	global_load_dwordx4 v[26:29], v[50:51], off
	v_mfma_f32_16x16x32_bf16 v[140:143], v[124:127], v[162:165], v[166:169]
	ds_write_b64 v147, v[144:145]
	v_mul_f32_e32 v144, v123, v63
	v_mul_f32_e32 v145, v123, v64
	v_mul_f32_e32 v162, v123, v74
	v_exp_f32_e32 v144, v144
	v_exp_f32_e32 v145, v145
	v_exp_f32_e32 v162, v162
	v_mfma_f32_16x16x32_bf16 v[152:155], v[124:127], v[170:173], v[174:177]
	v_mul_f32_e32 v128, v144, v128
	v_mul_f32_e32 v129, v145, v129
	v_mul_f32_e32 v131, v162, v131
	v_cvt_pk_bf16_f32 v128, v128, v129
	v_cvt_pk_bf16_f32 v129, v130, v131
	ds_write_b64 v147, v[128:129] offset:4352
	v_mul_f32_e32 v128, v123, v76
	v_mul_f32_e32 v129, v123, v77
	v_mul_f32_e32 v130, v123, v78
	v_mul_f32_e32 v131, v123, v79
	v_exp_f32_e32 v128, v128
	v_exp_f32_e32 v129, v129
	v_exp_f32_e32 v130, v130
	v_exp_f32_e32 v131, v131
	v_mul_f32_e32 v128, v128, v132
	v_mul_f32_e32 v129, v129, v133
	v_mul_f32_e32 v130, v130, v134
	v_mul_f32_e32 v131, v131, v135
	v_cvt_pk_bf16_f32 v128, v128, v129
	v_cvt_pk_bf16_f32 v129, v130, v131
	ds_write_b64 v147, v[128:129] offset:8704
	v_mul_f32_e32 v128, v123, v80
	v_mul_f32_e32 v129, v123, v81
	v_mul_f32_e32 v130, v123, v82
	v_mul_f32_e32 v131, v123, v83
	v_exp_f32_e32 v128, v128
	v_exp_f32_e32 v129, v129
	v_exp_f32_e32 v130, v130
	v_exp_f32_e32 v131, v131
	v_mul_f32_e32 v128, v128, v136
	v_mul_f32_e32 v129, v129, v137
	v_mul_f32_e32 v130, v130, v138
	v_mul_f32_e32 v131, v131, v139
	v_cvt_pk_bf16_f32 v128, v128, v129
	v_cvt_pk_bf16_f32 v129, v130, v131
	v_add_u32_e32 v130, v45, v73
	ds_write_b64 v130, v[128:129]
	v_mul_f32_e32 v128, v123, v84
	v_mul_f32_e32 v129, v123, v85
	v_mul_f32_e32 v130, v123, v86
	v_mul_f32_e32 v131, v123, v87
	v_exp_f32_e32 v128, v128
	v_exp_f32_e32 v129, v129
	v_exp_f32_e32 v130, v130
	v_exp_f32_e32 v131, v131
	v_mul_f32_e32 v128, v128, v140
	v_mul_f32_e32 v129, v129, v141
	v_mul_f32_e32 v130, v130, v142
	v_mul_f32_e32 v131, v131, v143
	v_cvt_pk_bf16_f32 v128, v128, v129
	v_cvt_pk_bf16_f32 v129, v130, v131
	ds_write_b64 v147, v[128:129] offset:17408
	v_mul_f32_e32 v128, v123, v88
	v_mul_f32_e32 v129, v123, v89
	v_mul_f32_e32 v130, v123, v90
	v_mul_f32_e32 v131, v123, v91
	v_exp_f32_e32 v128, v128
	v_exp_f32_e32 v129, v129
	v_exp_f32_e32 v130, v130
	v_exp_f32_e32 v131, v131
	v_mul_f32_e32 v128, v128, v152
	v_mul_f32_e32 v129, v129, v153
	v_mul_f32_e32 v130, v130, v154
	v_mul_f32_e32 v131, v131, v155
	v_cvt_pk_bf16_f32 v128, v128, v129
	v_cvt_pk_bf16_f32 v129, v130, v131
	ds_write_b64 v147, v[128:129] offset:21760
	v_mul_f32_e32 v128, v123, v92
	v_mul_f32_e32 v129, v123, v93
	v_mul_f32_e32 v130, v123, v94
	v_mul_f32_e32 v131, v123, v95
	s_waitcnt lgkmcnt(7)
	v_mfma_f32_16x16x32_bf16 v[156:159], v[124:127], v[202:205], v[206:209]
	v_exp_f32_e32 v128, v128
	v_exp_f32_e32 v129, v129
	v_exp_f32_e32 v130, v130
	v_exp_f32_e32 v131, v131
	s_waitcnt lgkmcnt(6)
	v_mfma_f32_16x16x32_bf16 v[124:127], v[124:127], v[210:213], v[198:201]
	s_nop 1
	v_mul_f32_e32 v128, v128, v156
	v_mul_f32_e32 v129, v129, v157
	v_mul_f32_e32 v130, v130, v158
	v_mul_f32_e32 v131, v131, v159
	v_cvt_pk_bf16_f32 v128, v128, v129
	v_cvt_pk_bf16_f32 v129, v130, v131
	ds_write_b64 v147, v[128:129] offset:26112
	v_mul_f32_e32 v128, v123, v102
	v_mul_f32_e32 v129, v123, v103
	v_mul_f32_e32 v130, v123, v104
	v_mul_f32_e32 v123, v123, v105
	v_exp_f32_e32 v128, v128
	v_exp_f32_e32 v129, v129
	v_exp_f32_e32 v130, v130
	v_exp_f32_e32 v123, v123
	v_mul_f32_e32 v124, v128, v124
	v_mul_f32_e32 v125, v129, v125
	v_mul_f32_e32 v126, v130, v126
	v_mul_f32_e32 v123, v123, v127
	v_cvt_pk_bf16_f32 v124, v124, v125
	v_cvt_pk_bf16_f32 v125, v126, v123
	ds_write_b64 v99, v[124:125]
	s_waitcnt lgkmcnt(0)
	s_barrier
	ds_read_b128 v[124:127], v117
	ds_read_b64_tr_b16 v[128:129], v101
	ds_read_b64_tr_b16 v[130:131], v101 offset:576
	ds_read_b128 v[132:135], v117 offset:4352
	ds_read_b128 v[136:139], v117 offset:8704
	ds_read_b128 v[152:155], v107
	ds_read_b128 v[140:143], v117 offset:13056
	s_waitcnt lgkmcnt(4)
	v_mfma_f32_16x16x32_bf16 v[124:127], v[124:127], v[128:131], 0
	v_lshl_add_u64 v[144:145], s[14:15], 0, v[46:47]
	s_mov_b64 s[14:15], 0x6000000
	v_lshl_add_u64 v[50:51], v[50:51], 0, s[10:11]
	s_waitcnt lgkmcnt(3)
	v_mfma_f32_16x16x32_bf16 v[132:135], v[132:135], v[128:131], 0
	s_waitcnt lgkmcnt(2)
	v_mfma_f32_16x16x32_bf16 v[136:139], v[136:139], v[128:131], 0
	s_waitcnt lgkmcnt(0)
	v_mfma_f32_16x16x32_bf16 v[128:131], v[140:143], v[128:131], 0
	ds_read_b128 v[140:143], v109
	ds_read_b64_tr_b16 v[156:157], v119
	ds_read_b64_tr_b16 v[158:159], v119 offset:576
	ds_read_b64_tr_b16 v[162:163], v120
	ds_read_b64_tr_b16 v[164:165], v120 offset:576
	s_waitcnt lgkmcnt(2)
	v_mfma_f32_16x16x32_bf16 v[124:127], v[152:155], v[156:159], v[124:127]
	ds_read_b128 v[152:155], v110
	s_waitcnt lgkmcnt(0)
	v_mfma_f32_16x16x32_bf16 v[136:139], v[152:155], v[156:159], v[136:139]
	ds_read_b128 v[152:155], v112
	v_mfma_f32_16x16x32_bf16 v[132:135], v[140:143], v[156:159], v[132:135]
	ds_read_b128 v[140:143], v111
	s_waitcnt lgkmcnt(1)
	v_mfma_f32_16x16x32_bf16 v[124:127], v[152:155], v[162:165], v[124:127]
	ds_read_b128 v[152:155], v114
	s_waitcnt lgkmcnt(0)
	v_mfma_f32_16x16x32_bf16 v[136:139], v[152:155], v[162:165], v[136:139]
	ds_read_b128 v[152:155], v100
	v_mfma_f32_16x16x32_bf16 v[128:131], v[140:143], v[156:159], v[128:131]
	ds_read_b128 v[140:143], v113
	s_waitcnt lgkmcnt(0)
	v_mfma_f32_16x16x32_bf16 v[132:135], v[140:143], v[162:165], v[132:135]
	ds_read_b128 v[140:143], v115
	s_waitcnt lgkmcnt(0)
	v_mfma_f32_16x16x32_bf16 v[128:131], v[140:143], v[162:165], v[128:131]
	ds_read_b64_tr_b16 v[140:141], v121
	ds_read_b64_tr_b16 v[142:143], v121 offset:576
	ds_read_b128 v[156:159], v108
	s_waitcnt lgkmcnt(1)
	v_mfma_f32_16x16x32_bf16 v[124:127], v[152:155], v[140:143], v[124:127]
	ds_read_b128 v[152:155], v116
	s_waitcnt lgkmcnt(1)
	v_mfma_f32_16x16x32_bf16 v[132:135], v[156:159], v[140:143], v[132:135]
	ds_read_b128 v[156:159], v118
	s_waitcnt lgkmcnt(1)
	v_mfma_f32_16x16x32_bf16 v[136:139], v[152:155], v[140:143], v[136:139]
	s_waitcnt lgkmcnt(0)
	v_mfma_f32_16x16x32_bf16 v[128:131], v[156:159], v[140:143], v[128:131]
	ds_read_b128 v[140:143], v106 offset:18432
	ds_read_b128 v[152:155], v106 offset:18496
	s_waitcnt vmcnt(3) lgkmcnt(1)
	v_mfma_f32_16x16x32_bf16 v[124:127], v[140:143], v[38:41], v[124:127]
	ds_read_b128 v[140:143], v106 offset:20736
	ds_read_b128 v[156:159], v106 offset:20800
	s_waitcnt lgkmcnt(1)
	v_mfma_f32_16x16x32_bf16 v[132:135], v[140:143], v[38:41], v[132:135]
	ds_read_b128 v[140:143], v106 offset:23040
	ds_read_b128 v[162:165], v106 offset:23104
	s_waitcnt lgkmcnt(1)
	v_mfma_f32_16x16x32_bf16 v[136:139], v[140:143], v[38:41], v[136:139]
	ds_read_b128 v[140:143], v106 offset:25344
	ds_read_b128 v[166:169], v106 offset:25408
	s_waitcnt lgkmcnt(1)
	v_mfma_f32_16x16x32_bf16 v[38:41], v[140:143], v[38:41], v[128:131]
	s_waitcnt vmcnt(2)
	v_mfma_f32_16x16x32_bf16 v[124:127], v[152:155], v[34:37], v[124:127]
	v_mfma_f32_16x16x32_bf16 v[128:131], v[156:159], v[34:37], v[132:135]
	v_mfma_f32_16x16x32_bf16 v[132:135], v[162:165], v[34:37], v[136:139]
	s_waitcnt lgkmcnt(0)
	v_mfma_f32_16x16x32_bf16 v[34:37], v[166:169], v[34:37], v[38:41]
	s_nop 2
	ds_read_b128 v[38:41], v106 offset:36864
	ds_read_b128 v[136:139], v106 offset:36928
	s_waitcnt vmcnt(1) lgkmcnt(1)
	v_mfma_f32_16x16x32_bf16 v[38:41], v[38:41], v[30:33], v[124:127]
	s_nop 2
	ds_read_b128 v[124:127], v106 offset:39168
	ds_read_b128 v[140:143], v106 offset:39232
	s_waitcnt lgkmcnt(1)
	v_mfma_f32_16x16x32_bf16 v[124:127], v[124:127], v[30:33], v[128:131]
	s_nop 2
	ds_read_b128 v[128:131], v106 offset:41472
	ds_read_b128 v[152:155], v106 offset:41536
	s_waitcnt lgkmcnt(1)
	v_mfma_f32_16x16x32_bf16 v[128:131], v[128:131], v[30:33], v[132:135]
	s_nop 2
	ds_read_b128 v[132:135], v106 offset:43776
	ds_read_b128 v[156:159], v106 offset:43840
	s_waitcnt lgkmcnt(1)
	v_mfma_f32_16x16x32_bf16 v[30:33], v[132:135], v[30:33], v[34:37]
	s_waitcnt vmcnt(0)
	v_mfma_f32_16x16x32_bf16 v[34:37], v[136:139], v[26:29], v[38:41]
	v_mfma_f32_16x16x32_bf16 v[38:41], v[140:143], v[26:29], v[124:127]
	v_mfma_f32_16x16x32_bf16 v[124:127], v[152:155], v[26:29], v[128:131]
	v_lshl_add_u64 v[152:153], v[48:49], 0, s[80:81]
	s_lshl_b32 s80, s9, 7
	s_waitcnt lgkmcnt(0)
	v_mfma_f32_16x16x32_bf16 v[26:29], v[156:159], v[26:29], v[30:33]
	s_nop 2
	global_load_dwordx4 v[2:5], v236, s[100:101]
	global_load_dwordx4 v[6:9], v237, s[100:101]
	global_load_dwordx4 v[22:25], v238, s[100:101]
	v_lshlrev_b64 v[30:31], 7, v[144:145]
	v_lshl_add_u64 v[30:31], s[16:17], 0, v[30:31]
	v_lshl_add_u64 v[30:31], v[30:31], 0, v[0:1]
	v_lshl_add_u64 v[128:129], v[30:31], 0, s[14:15]
	v_add_co_u32_e32 v30, vcc, s8, v30
	v_lshlrev_b64 v[144:145], 11, v[144:145]
	s_nop 0
	v_addc_co_u32_e32 v31, vcc, 0, v31, vcc
	global_load_dwordx4 v[30:33], v[30:31], off
	s_nop 0
	global_load_dwordx4 v[128:131], v[128:129], off offset:16
	s_barrier
	global_load_dwordx4 v[18:21], v239, s[100:101]
	global_load_dwordx4 v[10:13], v240, s[100:101]
	global_load_dwordx4 v[14:17], v241, s[100:101]
	ds_write2_b32 v122, v34, v35 offset1:68
	ds_write2_b32 v122, v36, v37 offset0:136 offset1:204
	v_add_u32_e32 v34, 0x1000, v122
	ds_write2_b32 v34, v38, v39 offset0:64 offset1:132
	v_add_u32_e32 v34, 0x1200, v122
	ds_write2_b32 v34, v40, v41 offset0:72 offset1:140
	v_add_u32_e32 v34, 0x2000, v122
	ds_write2_b32 v34, v124, v125 offset0:128 offset1:196
	v_add_u32_e32 v34, 0x2400, v122
	ds_write2_b32 v34, v126, v127 offset0:8 offset1:76
	v_add_u32_e32 v34, 0x3200, v122
	ds_write2_b32 v34, v26, v27 offset0:64 offset1:132
	v_add_u32_e32 v26, 0x3400, v122
	ds_write2_b32 v26, v28, v29 offset0:72 offset1:140
	s_waitcnt lgkmcnt(0)
	s_barrier
	ds_read_b128 v[38:41], v70
	ds_read_b128 v[124:127], v70 offset:16
	ds_read_b128 v[132:135], v70 offset:32
	ds_read_b128 v[136:139], v70 offset:48
	v_lshl_add_u64 v[144:145], s[74:75], 0, v[144:145]
	s_waitcnt lgkmcnt(3)
	v_pk_mul_f32 v[140:141], v[40:41], v[40:41]
	v_pk_mul_f32 v[142:143], v[38:39], v[38:39]
	v_lshl_add_u64 v[144:145], v[144:145], 0, s[80:81]
	v_pk_mov_b32 v[154:155], v[142:143], v[140:141] op_sel:[1,0]
	v_mov_b32_e32 v143, v141
	v_pk_add_f32 v[156:157], v[154:155], v[142:143]
	s_waitcnt lgkmcnt(2)
	v_pk_mul_f32 v[140:141], v[126:127], v[126:127]
	v_pk_mul_f32 v[142:143], v[124:125], v[124:125]
	s_waitcnt lgkmcnt(0)
	v_mul_f32_e32 v123, v136, v136
	v_pk_mov_b32 v[154:155], v[142:143], v[140:141] op_sel:[1,0]
	v_mov_b32_e32 v143, v141
	v_pk_add_f32 v[158:159], v[154:155], v[142:143]
	v_mul_f32_e32 v147, v137, v137
	v_pk_add_f32 v[156:157], v[156:157], v[156:157] op_sel:[0,1] op_sel_hi:[1,0]
	v_pk_add_f32 v[158:159], v[158:159], v[158:159] op_sel:[0,1] op_sel_hi:[1,0]
	v_mov_b32_e32 v157, v123
	v_mov_b32_e32 v159, v147
	v_pk_add_f32 v[156:157], v[156:157], v[158:159]
	v_mul_f32_e32 v158, v133, v133
	v_mul_f32_e32 v160, v138, v138
	v_pk_fma_f32 v[158:159], v[132:133], v[132:133], v[158:159] op_sel_hi:[1,1,0]
	v_mul_f32_e32 v164, v139, v139
	v_mov_b32_e32 v159, v160
	v_mul_f32_e32 v160, v135, v135
	v_pk_fma_f32 v[162:163], v[134:135], v[134:135], v[160:161] op_sel_hi:[1,1,0]
	v_lshl_add_u64 v[144:145], v[144:145], 0, v[0:1]
	v_mov_b32_e32 v163, v164
	v_pk_add_f32 v[158:159], v[158:159], v[162:163]
	s_mov_b32 s8, s3
	v_pk_add_f32 v[156:157], v[156:157], v[158:159]
	s_waitcnt vmcnt(4)
	v_lshlrev_b32_e32 v158, 16, v30
	v_add_f32_e32 v123, v156, v157
	ds_bpermute_b32 v147, v97, v123
	v_and_b32_e32 v159, 0xffff0000, v30
	v_lshlrev_b32_e32 v30, 16, v31
	v_and_b32_e32 v31, 0xffff0000, v31
	v_lshlrev_b32_e32 v162, 16, v32
	s_waitcnt lgkmcnt(0)
	v_add_f32_e32 v123, v123, v147
	ds_bpermute_b32 v147, v98, v123
	v_and_b32_e32 v163, 0xffff0000, v32
	v_lshlrev_b32_e32 v32, 16, v33
	v_and_b32_e32 v33, 0xffff0000, v33
	s_waitcnt lgkmcnt(0)
	v_add_f32_e32 v123, v123, v147
	v_fmamk_f32 v123, v123, 0x3c800000, v178
	v_mul_f32_e32 v147, 0x4b800000, v123
	v_cmp_gt_f32_e32 vcc, s22, v123
	s_nop 1
	v_cndmask_b32_e32 v123, v123, v147, vcc
	v_rsq_f32_e32 v123, v123
	s_nop 0
	v_mul_f32_e32 v147, 0x45800000, v123
	v_cndmask_b32_e32 v156, v123, v147, vcc
	v_pk_mul_f32 v[40:41], v[40:41], v[156:157] op_sel_hi:[1,0]
	v_pk_mul_f32 v[38:39], v[38:39], v[156:157] op_sel_hi:[1,0]
	v_pk_mul_f32 v[28:29], v[222:223], v[40:41]
	v_pk_mul_f32 v[26:27], v[220:221], v[38:39]
	v_pk_mul_f32 v[28:29], v[28:29], v[30:31]
	v_pk_mul_f32 v[30:31], v[126:127], v[156:157] op_sel_hi:[1,0]
	v_pk_mul_f32 v[38:39], v[124:125], v[156:157] op_sel_hi:[1,0]
	v_pk_mul_f32 v[30:31], v[226:227], v[30:31]
	v_pk_mul_f32 v[34:35], v[224:225], v[38:39]
	v_pk_mul_f32 v[26:27], v[26:27], v[158:159]
	v_pk_mul_f32 v[30:31], v[30:31], v[32:33]
	v_pk_mul_f32 v[32:33], v[34:35], v[162:163]
	v_cvt_pk_bf16_f32 v26, v26, v27
	v_cvt_pk_bf16_f32 v27, v28, v29
	v_cvt_pk_bf16_f32 v28, v32, v33
	v_cvt_pk_bf16_f32 v29, v30, v31
	v_pk_mul_f32 v[34:35], v[134:135], v[156:157] op_sel_hi:[1,0]
	v_pk_mul_f32 v[36:37], v[132:133], v[156:157] op_sel_hi:[1,0]
	global_store_dwordx4 v[144:145], v[26:29], off
	s_waitcnt vmcnt(4)
	v_pk_mul_f32 v[36:37], v[228:229], v[36:37]
	v_pk_mul_f32 v[34:35], v[230:231], v[34:35]
	v_lshlrev_b32_e32 v26, 16, v128
	v_and_b32_e32 v27, 0xffff0000, v128
	v_lshlrev_b32_e32 v28, 16, v129
	v_and_b32_e32 v29, 0xffff0000, v129
	v_pk_mul_f32 v[28:29], v[34:35], v[28:29]
	v_pk_mul_f32 v[26:27], v[36:37], v[26:27]
	v_pk_mul_f32 v[34:35], v[138:139], v[156:157] op_sel_hi:[1,0]
	v_pk_mul_f32 v[36:37], v[136:137], v[156:157] op_sel_hi:[1,0]
	v_lshlrev_b32_e32 v30, 16, v130
	v_and_b32_e32 v31, 0xffff0000, v130
	v_lshlrev_b32_e32 v32, 16, v131
	v_and_b32_e32 v33, 0xffff0000, v131
	v_pk_mul_f32 v[36:37], v[232:233], v[36:37]
	v_pk_mul_f32 v[34:35], v[234:235], v[34:35]
	v_pk_mul_f32 v[30:31], v[36:37], v[30:31]
	v_pk_mul_f32 v[32:33], v[34:35], v[32:33]
	v_cvt_pk_bf16_f32 v26, v26, v27
	v_cvt_pk_bf16_f32 v27, v28, v29
	v_cvt_pk_bf16_f32 v28, v30, v31
	v_cvt_pk_bf16_f32 v29, v32, v33
	s_and_b64 vcc, exec, s[12:13]
	global_store_dwordx4 v[144:145], v[26:29], off offset:16
	s_barrier
	s_cbranch_vccnz .LBB0_459
.LBB0_457:
	s_add_i32 s3, s8, s2
	s_cmpk_gt_i32 s3, 0x7ff
	s_cselect_b64 s[12:13], -1, 0
	s_cmpk_lt_i32 s3, 0x800
	s_cselect_b32 s14, s3, -1
	s_and_b32 s9, s8, 7
	s_cmp_eq_u32 s9, 1
	s_cselect_b64 vcc, -1, 0
	s_cmp_lg_u32 s9, 2
	v_cndmask_b32_e32 v26, v181, v182, vcc
	s_cselect_b64 vcc, -1, 0
	s_cmp_lg_u32 s9, 3
	v_cndmask_b32_e32 v26, v183, v26, vcc
	s_cselect_b64 vcc, -1, 0
	s_cmp_lg_u32 s9, 4
	v_cndmask_b32_e32 v26, v184, v26, vcc
	s_cselect_b64 vcc, -1, 0
	s_cmp_lg_u32 s9, 5
	v_cndmask_b32_e32 v26, v185, v26, vcc
	s_cselect_b64 vcc, -1, 0
	s_cmp_lg_u32 s9, 6
	v_cndmask_b32_e32 v26, v186, v26, vcc
	s_cselect_b64 vcc, -1, 0
	s_cmp_lg_u32 s9, 7
	v_cndmask_b32_e32 v26, v187, v26, vcc
	s_cselect_b64 vcc, -1, 0
	v_cndmask_b32_e32 v123, v188, v26, vcc
	v_mul_f32_e32 v26, v123, v43
	v_exp_f32_e32 v26, v26
	v_mul_f32_e32 v27, v123, v52
	v_exp_f32_e32 v38, v27
	s_waitcnt vmcnt(2)
	v_lshlrev_b32_e32 v30, 16, v2
	v_and_b32_e32 v31, 0xffff0000, v2
	v_lshlrev_b32_e32 v32, 16, v3
	v_and_b32_e32 v33, 0xffff0000, v3
	v_lshlrev_b32_e32 v34, 16, v4
	v_and_b32_e32 v35, 0xffff0000, v4
	v_lshlrev_b32_e32 v36, 16, v5
	v_and_b32_e32 v37, 0xffff0000, v5
	v_pk_mul_f32 v[28:29], v[26:27], v[32:33] op_sel_hi:[0,1]
	v_pk_mul_f32 v[40:41], v[26:27], v[30:31] op_sel_hi:[0,1]
	v_pk_mul_f32 v[124:125], v[26:27], v[36:37] op_sel_hi:[0,1]
	v_pk_mul_f32 v[126:127], v[26:27], v[34:35] op_sel_hi:[0,1]
	v_cvt_pk_bf16_f32 v26, v40, v41
	v_cvt_pk_bf16_f32 v27, v28, v29
	v_cvt_pk_bf16_f32 v28, v126, v127
	v_cvt_pk_bf16_f32 v29, v124, v125
	ds_write_b128 v53, v[26:29] offset:18432
	v_pk_mul_f32 v[28:29], v[38:39], v[32:33] op_sel_hi:[0,1]
	v_pk_mul_f32 v[26:27], v[38:39], v[30:31] op_sel_hi:[0,1]
	v_pk_mul_f32 v[30:31], v[38:39], v[36:37] op_sel_hi:[0,1]
	v_pk_mul_f32 v[32:33], v[38:39], v[34:35] op_sel_hi:[0,1]
	v_cvt_pk_bf16_f32 v26, v26, v27
	v_cvt_pk_bf16_f32 v27, v28, v29
	v_cvt_pk_bf16_f32 v28, v32, v33
	v_cvt_pk_bf16_f32 v29, v30, v31
	ds_write_b128 v53, v[2:5]
	ds_write_b128 v53, v[26:29] offset:36864
	ds_write_b128 v53, v[6:9] offset:55296
	ds_write_b128 v54, v[22:25]
	v_mul_f32_e32 v26, v123, v55
	v_exp_f32_e32 v26, v26
	v_mul_f32_e32 v27, v123, v56
	v_exp_f32_e32 v38, v27
	v_lshlrev_b32_e32 v30, 16, v18
	v_and_b32_e32 v31, 0xffff0000, v18
	v_lshlrev_b32_e32 v32, 16, v19
	v_and_b32_e32 v33, 0xffff0000, v19
	v_lshlrev_b32_e32 v34, 16, v20
	v_and_b32_e32 v35, 0xffff0000, v20
	v_lshlrev_b32_e32 v36, 16, v21
	v_and_b32_e32 v37, 0xffff0000, v21
	v_pk_mul_f32 v[28:29], v[26:27], v[32:33] op_sel_hi:[0,1]
	v_pk_mul_f32 v[40:41], v[26:27], v[30:31] op_sel_hi:[0,1]
	v_pk_mul_f32 v[124:125], v[26:27], v[36:37] op_sel_hi:[0,1]
	v_pk_mul_f32 v[126:127], v[26:27], v[34:35] op_sel_hi:[0,1]
	v_cvt_pk_bf16_f32 v26, v40, v41
	v_cvt_pk_bf16_f32 v27, v28, v29
	v_cvt_pk_bf16_f32 v28, v126, v127
	v_cvt_pk_bf16_f32 v29, v124, v125
	ds_write_b128 v57, v[26:29] offset:18432
	v_pk_mul_f32 v[28:29], v[38:39], v[32:33] op_sel_hi:[0,1]
	v_pk_mul_f32 v[26:27], v[38:39], v[30:31] op_sel_hi:[0,1]
	v_pk_mul_f32 v[30:31], v[38:39], v[36:37] op_sel_hi:[0,1]
	v_pk_mul_f32 v[32:33], v[38:39], v[34:35] op_sel_hi:[0,1]
	v_cvt_pk_bf16_f32 v26, v26, v27
	v_cvt_pk_bf16_f32 v27, v28, v29
	v_cvt_pk_bf16_f32 v28, v32, v33
	v_cvt_pk_bf16_f32 v29, v30, v31
	s_cmp_lt_i32 s14, 0
	ds_write_b128 v57, v[18:21]
	ds_write_b128 v57, v[26:29] offset:36864
	ds_write_b128 v57, v[10:13] offset:55296
	ds_write_b128 v58, v[14:17]
	s_waitcnt lgkmcnt(0)
	s_barrier
	s_cmpk_lt_i32 s3, 0x800
	s_cselect_b32 s14, s3, s8
	s_lshr_b32 s15, s14, 3
	s_lshl_b32 s15, s15, 14
	s_and_b32 s14, s14, 7
	s_lshl_b32 s14, s14, 22
	s_add_u32 s14, s14, s15
	s_add_u32 s100, s86, s14
	s_addc_u32 s101, s87, 0
	s_and_b32 s14, s8, 7
	s_lshl_b32 s14, s14, 8
	s_mov_b32 s15, 0
	v_lshl_add_u64 v[244:245], v[48:49], 0, s[14:15]
	global_load_dwordx4 v[220:223], v[244:245], off
	global_load_dwordx4 v[224:227], v[244:245], off offset:16
	global_load_dwordx4 v[228:231], v[244:245], off offset:32
	global_load_dwordx4 v[232:235], v[244:245], off offset:48
	s_branch .LBB0_456
